# k27_pack2
# baseline (speedup 1.0000x reference)
; DI f32x16 mfma32(bf16x8 a, bf16x8 b, f32x16 c) { return __builtin_amdgcn_mfma_f32_32x32x16_bf16(a, b, c, 0, 0, 0); }
; DI unsigned pack2(float a, float b) { return (unsigned)f2bf(a) | ((unsigned)f2bf(b) << 16); }
; template <bool MLA>
; DI void attn_task(const Params& p, char* smem, int b, int head, int qt) {
;     ...
; #pragma unroll
;       for (int k2 = 0; k2 < 2; ++k2)
; #pragma unroll
;         for (int i = 0; i < 16; ++i) { const float pv = __builtin_amdgcn_exp2f(s[k2][i] - mn); l += pv; s[k2][i] = pv; }
; #pragma unroll
;       for (int k2 = 0; k2 < 2; ++k2)
; #pragma unroll
;         for (int st = 0; st < 2; ++st) {
;           const bf16x8 pb = pack8(s[k2][8 * st + 0], s[k2][8 * st + 1], s[k2][8 * st + 2], s[k2][8 * st + 3],
;                                   s[k2][8 * st + 4], s[k2][8 * st + 5], s[k2][8 * st + 6], s[k2][8 * st + 7]);
; #pragma unroll
;           for (int dt = 0; dt < 2; ++dt) {
;             const bf16x8 va = frag_tr_perm(Vs, VLD, k2 * 32 + st * 16, dt * 32, lane);
;             oacc[dt] = mfma32(va, pb, oacc[dt]);
;           }
;         }
.LBB0_368:
	v_sub_f32_e32 v48, v48, v106
	v_exp_f32_e32 v48, v48
	v_sub_f32_e32 v49, v49, v106
	v_sub_f32_e32 v50, v50, v106
	v_exp_f32_e32 v49, v49
	v_exp_f32_e32 v50, v50
	v_sub_f32_e32 v51, v51, v106
	v_exp_f32_e32 v51, v51
	v_sub_f32_e32 v52, v52, v106
	v_sub_f32_e32 v32, v32, v106
	v_add_f32_e32 v105, v105, v48
	v_exp_f32_e32 v52, v52
	v_sub_f32_e32 v53, v53, v106
	v_exp_f32_e32 v107, v32
	v_sub_f32_e32 v32, v33, v106
	v_add_f32_e32 v105, v49, v105
	v_exp_f32_e32 v53, v53
	v_sub_f32_e32 v54, v54, v106
	v_exp_f32_e32 v133, v32
	v_sub_f32_e32 v32, v34, v106
	v_add_f32_e32 v105, v50, v105
	v_exp_f32_e32 v54, v54
	v_sub_f32_e32 v55, v55, v106
	v_exp_f32_e32 v134, v32
	v_sub_f32_e32 v32, v35, v106
	v_add_f32_e32 v105, v51, v105
	v_exp_f32_e32 v55, v55
	v_exp_f32_e32 v135, v32
	v_sub_f32_e32 v32, v36, v106
	v_add_f32_e32 v105, v52, v105
	v_exp_f32_e32 v136, v32
	v_add_u32_e32 v137, v119, v123
	v_add_f32_e32 v105, v53, v105
	v_cvt_pk_bf16_f32 v32, v48, v49
	v_cvt_pk_bf16_f32 v33, v50, v51
	ds_read_b64_tr_b16 v[48:49], v137 offset:9216
	ds_read_b64_tr_b16 v[50:51], v137 offset:10752
	v_add_f32_e32 v105, v54, v105
	v_add_f32_e32 v105, v55, v105
	v_sub_f32_e32 v57, v57, v106
	v_sub_f32_e32 v36, v37, v106
	v_cvt_pk_bf16_f32 v34, v52, v53
	v_cvt_pk_bf16_f32 v35, v54, v55
	ds_read_b64_tr_b16 v[54:55], v137 offset:10816
	ds_read_b64_tr_b16 v[52:53], v137 offset:9280
	v_sub_f32_e32 v56, v56, v106
	v_exp_f32_e32 v57, v57
	v_sub_f32_e32 v59, v59, v106
	v_exp_f32_e32 v56, v56
	v_sub_f32_e32 v58, v58, v106
	v_exp_f32_e32 v59, v59
	v_sub_f32_e32 v61, v61, v106
	v_exp_f32_e32 v58, v58
	v_sub_f32_e32 v60, v60, v106
	v_exp_f32_e32 v61, v61
	v_sub_f32_e32 v63, v63, v106
	s_waitcnt lgkmcnt(2)
	v_mfma_f32_32x32x16_bf16 v[16:31], v[48:51], v[32:35], v[16:31]
	v_exp_f32_e32 v138, v36
	v_sub_f32_e32 v36, v38, v106
	v_exp_f32_e32 v60, v60
	v_sub_f32_e32 v62, v62, v106
	v_exp_f32_e32 v63, v63
	v_exp_f32_e32 v139, v36
	v_sub_f32_e32 v36, v39, v106
	v_exp_f32_e32 v62, v62
	v_exp_f32_e32 v140, v36
	v_sub_f32_e32 v36, v40, v106
	s_waitcnt lgkmcnt(0)
	v_mfma_f32_32x32x16_bf16 v[0:15], v[52:55], v[32:35], v[0:15]
	v_exp_f32_e32 v141, v36
	ds_read_b64_tr_b16 v[36:37], v137 offset:12288
	ds_read_b64_tr_b16 v[38:39], v137 offset:13824
	v_cvt_pk_bf16_f32 v32, v56, v57
	v_cvt_pk_bf16_f32 v33, v58, v59
	ds_read_b64_tr_b16 v[50:51], v137 offset:13888
	ds_read_b64_tr_b16 v[48:49], v137 offset:12352
	v_cvt_pk_bf16_f32 v34, v60, v61
	v_cvt_pk_bf16_f32 v35, v62, v63
	s_waitcnt lgkmcnt(2)
	s_nop 0
	v_mfma_f32_32x32x16_bf16 v[16:31], v[36:39], v[32:35], v[16:31]
	v_sub_f32_e32 v36, v41, v106
	v_exp_f32_e32 v52, v36
	v_sub_f32_e32 v36, v42, v106
	v_exp_f32_e32 v53, v36
	v_sub_f32_e32 v36, v43, v106
	v_exp_f32_e32 v54, v36
	ds_read_b64_tr_b16 v[36:37], v137 offset:15360
	ds_read_b64_tr_b16 v[38:39], v137 offset:16896
	s_waitcnt lgkmcnt(2)
	v_mfma_f32_32x32x16_bf16 v[0:15], v[48:51], v[32:35], v[0:15]
	v_cvt_pk_bf16_f32 v32, v107, v133
	v_cvt_pk_bf16_f32 v33, v134, v135
	v_cvt_pk_bf16_f32 v34, v136, v138
	v_cvt_pk_bf16_f32 v35, v139, v140
	ds_read_b64_tr_b16 v[42:43], v137 offset:16960
	ds_read_b64_tr_b16 v[40:41], v137 offset:15424
	s_waitcnt lgkmcnt(2)
	v_mfma_f32_32x32x16_bf16 v[16:31], v[36:39], v[32:35], v[16:31]
	v_sub_f32_e32 v36, v45, v106
	v_exp_f32_e32 v45, v36
	v_sub_f32_e32 v36, v46, v106
	v_sub_f32_e32 v44, v44, v106
	v_exp_f32_e32 v46, v36
	v_sub_f32_e32 v36, v47, v106
	v_exp_f32_e32 v44, v44
	v_exp_f32_e32 v47, v36
	s_waitcnt lgkmcnt(0)
	v_mfma_f32_32x32x16_bf16 v[0:15], v[40:43], v[32:35], v[0:15]
	ds_read_b64_tr_b16 v[36:37], v137 offset:18432
	ds_read_b64_tr_b16 v[38:39], v137 offset:19968
	v_cvt_pk_bf16_f32 v32, v141, v52
	v_cvt_pk_bf16_f32 v33, v53, v54
	v_cvt_pk_bf16_f32 v34, v44, v45
	v_add_f32_e32 v105, v56, v105
	v_cvt_pk_bf16_f32 v35, v46, v47
	ds_read_b64_tr_b16 v[42:43], v137 offset:20032
	ds_read_b64_tr_b16 v[40:41], v137 offset:18496
	s_waitcnt lgkmcnt(2)
	v_mfma_f32_32x32x16_bf16 v[16:31], v[36:39], v[32:35], v[16:31]
	v_add_f32_e32 v36, v57, v105
	v_add_f32_e32 v36, v58, v36
	v_add_f32_e32 v36, v59, v36
	v_add_f32_e32 v36, v60, v36
	v_add_f32_e32 v36, v61, v36
	v_add_f32_e32 v36, v62, v36
	v_add_f32_e32 v36, v63, v36
	s_waitcnt lgkmcnt(0)
	v_mfma_f32_32x32x16_bf16 v[0:15], v[40:43], v[32:35], v[0:15]
	v_add_f32_e32 v32, v107, v36
	v_add_f32_e32 v32, v133, v32
	v_add_f32_e32 v32, v134, v32
	v_add_f32_e32 v32, v135, v32
	v_add_f32_e32 v32, v136, v32
	v_add_f32_e32 v32, v138, v32
	v_add_f32_e32 v32, v139, v32
	v_add_f32_e32 v32, v140, v32
	v_add_f32_e32 v32, v141, v32
	v_add_f32_e32 v32, v52, v32
	v_add_f32_e32 v32, v53, v32
	v_add_f32_e32 v32, v54, v32
	v_add_f32_e32 v32, v44, v32
	v_add_f32_e32 v32, v45, v32
	v_add_f32_e32 v32, v46, v32
	v_add_f32_e32 v105, v47, v32

; DI f32x16 mfma32(bf16x8 a, bf16x8 b, f32x16 c) { return __builtin_amdgcn_mfma_f32_32x32x16_bf16(a, b, c, 0, 0, 0); }
; DI unsigned pack2(float a, float b) { return (unsigned)f2bf(a) | ((unsigned)f2bf(b) << 16); }
; template <bool MLA>
; DI void attn_task(const Params& p, char* smem, int b, int head, int qt) {
;     ...
; #pragma unroll
;       for (int k2 = 0; k2 < 2; ++k2)
; #pragma unroll
;         for (int i = 0; i < 16; ++i) { const float pv = __builtin_amdgcn_exp2f(s[k2][i] - mn); l += pv; s[k2][i] = pv; }
; #pragma unroll
;       for (int k2 = 0; k2 < 2; ++k2)
; #pragma unroll
;         for (int st = 0; st < 2; ++st) {
;           const bf16x8 pb = pack8(s[k2][8 * st + 0], s[k2][8 * st + 1], s[k2][8 * st + 2], s[k2][8 * st + 3],
;                                   s[k2][8 * st + 4], s[k2][8 * st + 5], s[k2][8 * st + 6], s[k2][8 * st + 7]);
; #pragma unroll
;           for (int dt = 0; dt < 2; ++dt) {
;             const bf16x8 va = frag_tr_perm(Vs, VLD, k2 * 32 + st * 16, dt * 32, lane);
;             oacc[dt] = mfma32(va, pb, oacc[dt]);
;           }
;         }
.LBB0_396:
	v_sub_f32_e32 v48, v48, v163
	v_exp_f32_e32 v48, v48
	v_sub_f32_e32 v49, v49, v163
	v_sub_f32_e32 v50, v50, v163
	v_exp_f32_e32 v49, v49
	v_exp_f32_e32 v50, v50
	v_sub_f32_e32 v51, v51, v163
	v_exp_f32_e32 v51, v51
	v_sub_f32_e32 v52, v52, v163
	v_sub_f32_e32 v32, v32, v163
	v_add_f32_e32 v162, v162, v48
	v_exp_f32_e32 v52, v52
	v_sub_f32_e32 v53, v53, v163
	v_exp_f32_e32 v164, v32
	v_sub_f32_e32 v32, v33, v163
	v_add_f32_e32 v162, v49, v162
	v_exp_f32_e32 v53, v53
	v_sub_f32_e32 v54, v54, v163
	v_exp_f32_e32 v165, v32
	v_sub_f32_e32 v32, v34, v163
	v_add_f32_e32 v162, v50, v162
	v_exp_f32_e32 v54, v54
	v_sub_f32_e32 v55, v55, v163
	v_exp_f32_e32 v166, v32
	v_sub_f32_e32 v32, v35, v163
	v_add_f32_e32 v162, v51, v162
	v_exp_f32_e32 v55, v55
	v_exp_f32_e32 v167, v32
	v_sub_f32_e32 v32, v36, v163
	v_add_f32_e32 v162, v52, v162
	v_exp_f32_e32 v168, v32
	v_add_u32_e32 v169, v119, v123
	v_add_f32_e32 v162, v53, v162
	v_cvt_pk_bf16_f32 v32, v48, v49
	v_cvt_pk_bf16_f32 v33, v50, v51
	ds_read_b64_tr_b16 v[48:49], v169 offset:13312
	ds_read_b64_tr_b16 v[50:51], v169 offset:14848
	v_add_f32_e32 v162, v54, v162
	v_add_f32_e32 v162, v55, v162
	v_sub_f32_e32 v57, v57, v163
	v_sub_f32_e32 v36, v37, v163
	v_cvt_pk_bf16_f32 v34, v52, v53
	v_cvt_pk_bf16_f32 v35, v54, v55
	ds_read_b64_tr_b16 v[54:55], v169 offset:14912
	ds_read_b64_tr_b16 v[52:53], v169 offset:13376
	v_sub_f32_e32 v56, v56, v163
	v_exp_f32_e32 v57, v57
	v_sub_f32_e32 v59, v59, v163
	v_exp_f32_e32 v56, v56
	v_sub_f32_e32 v58, v58, v163
	v_exp_f32_e32 v59, v59
	v_sub_f32_e32 v61, v61, v163
	v_exp_f32_e32 v58, v58
	v_sub_f32_e32 v60, v60, v163
	v_exp_f32_e32 v61, v61
	v_sub_f32_e32 v63, v63, v163
	s_waitcnt lgkmcnt(2)
	v_mfma_f32_32x32x16_bf16 v[16:31], v[48:51], v[32:35], v[16:31]
	v_exp_f32_e32 v170, v36
	v_sub_f32_e32 v36, v38, v163
	v_exp_f32_e32 v60, v60
	v_sub_f32_e32 v62, v62, v163
	v_exp_f32_e32 v63, v63
	v_exp_f32_e32 v171, v36
	v_sub_f32_e32 v36, v39, v163
	v_exp_f32_e32 v62, v62
	v_exp_f32_e32 v172, v36
	v_sub_f32_e32 v36, v40, v163
	s_waitcnt lgkmcnt(0)
	v_mfma_f32_32x32x16_bf16 v[0:15], v[52:55], v[32:35], v[0:15]
	v_exp_f32_e32 v173, v36
	ds_read_b64_tr_b16 v[36:37], v169 offset:16384
	ds_read_b64_tr_b16 v[38:39], v169 offset:17920
	v_cvt_pk_bf16_f32 v32, v56, v57
	v_cvt_pk_bf16_f32 v33, v58, v59
	ds_read_b64_tr_b16 v[50:51], v169 offset:17984
	ds_read_b64_tr_b16 v[48:49], v169 offset:16448
	v_cvt_pk_bf16_f32 v34, v60, v61
	v_cvt_pk_bf16_f32 v35, v62, v63
	s_waitcnt lgkmcnt(2)
	s_nop 0
	v_mfma_f32_32x32x16_bf16 v[16:31], v[36:39], v[32:35], v[16:31]
	v_sub_f32_e32 v36, v41, v163
	v_exp_f32_e32 v52, v36
	v_sub_f32_e32 v36, v42, v163
	v_exp_f32_e32 v53, v36
	v_sub_f32_e32 v36, v43, v163
	v_exp_f32_e32 v54, v36
	ds_read_b64_tr_b16 v[36:37], v169 offset:19456
	ds_read_b64_tr_b16 v[38:39], v169 offset:20992
	s_waitcnt lgkmcnt(2)
	v_mfma_f32_32x32x16_bf16 v[0:15], v[48:51], v[32:35], v[0:15]
	v_cvt_pk_bf16_f32 v32, v164, v165
	v_cvt_pk_bf16_f32 v33, v166, v167
	v_cvt_pk_bf16_f32 v34, v168, v170
	v_cvt_pk_bf16_f32 v35, v171, v172
	ds_read_b64_tr_b16 v[42:43], v169 offset:21056
	ds_read_b64_tr_b16 v[40:41], v169 offset:19520
	s_waitcnt lgkmcnt(2)
	v_mfma_f32_32x32x16_bf16 v[16:31], v[36:39], v[32:35], v[16:31]
	v_sub_f32_e32 v36, v45, v163
	v_exp_f32_e32 v45, v36
	v_sub_f32_e32 v36, v46, v163
	v_sub_f32_e32 v44, v44, v163
	v_exp_f32_e32 v46, v36
	v_sub_f32_e32 v36, v47, v163
	v_exp_f32_e32 v44, v44
	v_exp_f32_e32 v47, v36
	s_waitcnt lgkmcnt(0)
	v_mfma_f32_32x32x16_bf16 v[0:15], v[40:43], v[32:35], v[0:15]
	ds_read_b64_tr_b16 v[36:37], v169 offset:22528
	ds_read_b64_tr_b16 v[38:39], v169 offset:24064
	v_cvt_pk_bf16_f32 v32, v173, v52
	v_cvt_pk_bf16_f32 v33, v53, v54
	v_cvt_pk_bf16_f32 v34, v44, v45
	v_add_f32_e32 v162, v56, v162
	v_cvt_pk_bf16_f32 v35, v46, v47
	ds_read_b64_tr_b16 v[42:43], v169 offset:24128
	ds_read_b64_tr_b16 v[40:41], v169 offset:22592
	s_waitcnt lgkmcnt(2)
	v_mfma_f32_32x32x16_bf16 v[16:31], v[36:39], v[32:35], v[16:31]
	v_add_f32_e32 v36, v57, v162
	v_add_f32_e32 v36, v58, v36
	v_add_f32_e32 v36, v59, v36
	v_add_f32_e32 v36, v60, v36
	v_add_f32_e32 v36, v61, v36
	v_add_f32_e32 v36, v62, v36
	v_add_f32_e32 v36, v63, v36
	s_waitcnt lgkmcnt(0)
	v_mfma_f32_32x32x16_bf16 v[0:15], v[40:43], v[32:35], v[0:15]
	v_add_f32_e32 v32, v164, v36
	v_add_f32_e32 v32, v165, v32
	v_add_f32_e32 v32, v166, v32
	v_add_f32_e32 v32, v167, v32
	v_add_f32_e32 v32, v168, v32
	v_add_f32_e32 v32, v170, v32
	v_add_f32_e32 v32, v171, v32
	v_add_f32_e32 v32, v172, v32
	v_add_f32_e32 v32, v173, v32
	v_add_f32_e32 v32, v52, v32
	v_add_f32_e32 v32, v53, v32
	v_add_f32_e32 v32, v54, v32
	v_add_f32_e32 v32, v44, v32
	v_add_f32_e32 v32, v45, v32
	v_add_f32_e32 v32, v46, v32
	v_add_f32_e32 v162, v47, v32
